# convert tile loads 8 in flight, pool slab staging 10 loads in flight, shw weight loads hoisted per trip
# speedup vs baseline: 1.0207x; 1.0086x over previous
; #define LAS __attribute__((address_space(3)))
; DEVI void ph_prep(const int wv, const Params& p, int l, int nrows_pool, unsigned char* lds_raw) {
;     ...
;         const int t0 = r0 - sbase, lo_row = max(t0 - 8, 0), hi_row = min(t0 + 72, L), nchunks = (hi_row - lo_row) * 64;
;         __syncthreads();
;         for (int e = tid; e < nchunks; e += NTHREADS) { const int rr = e >> 6, cch = e & 63; *(LAS u32x4*)(slab + rr * 1024 + cch * 16) = *(const u32x4*)(Z + (size_t)(sbase + lo_row + rr) * ZM + C_PU + cch * 8); }
.LBB0_474:
	v_ashrrev_i32_e32 v5, 6, v4
	v_mov_b64_e32 v[6:7], s[24:25]
	v_add_u32_e32 v8, s8, v5
	v_lshlrev_b32_e32 v0, 1, v2
	v_mad_i64_i32 v[6:7], s[30:31], v8, s46, v[6:7]
	v_lshl_add_u64 v[6:7], v[6:7], 0, v[0:1]
	v_add_co_u32_e32 v6, vcc, 0x1000, v6
	v_add_u32_e32 v4, 0x200, v4
	s_nop 0
	v_addc_co_u32_e32 v7, vcc, 0, v7, vcc
	global_load_dwordx4 v[40:43], v[6:7], off offset:512
	v_lshl_add_u32 v80, v5, 10, v12
	v_ashrrev_i32_e32 v5, 6, v4
	v_mov_b64_e32 v[6:7], s[24:25]
	v_add_u32_e32 v8, s8, v5
	v_lshlrev_b32_e32 v0, 1, v2
	v_mad_i64_i32 v[6:7], s[30:31], v8, s46, v[6:7]
	v_lshl_add_u64 v[6:7], v[6:7], 0, v[0:1]
	v_add_co_u32_e32 v6, vcc, 0x1000, v6
	v_add_u32_e32 v4, 0x200, v4
	s_nop 0
	v_addc_co_u32_e32 v7, vcc, 0, v7, vcc
	global_load_dwordx4 v[44:47], v[6:7], off offset:512
	v_lshl_add_u32 v81, v5, 10, v12
	v_ashrrev_i32_e32 v5, 6, v4
	v_mov_b64_e32 v[6:7], s[24:25]
	v_add_u32_e32 v8, s8, v5
	v_lshlrev_b32_e32 v0, 1, v2
	v_mad_i64_i32 v[6:7], s[30:31], v8, s46, v[6:7]
	v_lshl_add_u64 v[6:7], v[6:7], 0, v[0:1]
	v_add_co_u32_e32 v6, vcc, 0x1000, v6
	v_add_u32_e32 v4, 0x200, v4
	s_nop 0
	v_addc_co_u32_e32 v7, vcc, 0, v7, vcc
	global_load_dwordx4 v[48:51], v[6:7], off offset:512
	v_lshl_add_u32 v82, v5, 10, v12
	v_ashrrev_i32_e32 v5, 6, v4
	v_mov_b64_e32 v[6:7], s[24:25]
	v_add_u32_e32 v8, s8, v5
	v_lshlrev_b32_e32 v0, 1, v2
	v_mad_i64_i32 v[6:7], s[30:31], v8, s46, v[6:7]
	v_lshl_add_u64 v[6:7], v[6:7], 0, v[0:1]
	v_add_co_u32_e32 v6, vcc, 0x1000, v6
	v_add_u32_e32 v4, 0x200, v4
	s_nop 0
	v_addc_co_u32_e32 v7, vcc, 0, v7, vcc
	global_load_dwordx4 v[52:55], v[6:7], off offset:512
	v_lshl_add_u32 v83, v5, 10, v12
	v_ashrrev_i32_e32 v5, 6, v4
	v_mov_b64_e32 v[6:7], s[24:25]
	v_add_u32_e32 v8, s8, v5
	v_lshlrev_b32_e32 v0, 1, v2
	v_mad_i64_i32 v[6:7], s[30:31], v8, s46, v[6:7]
	v_lshl_add_u64 v[6:7], v[6:7], 0, v[0:1]
	v_add_co_u32_e32 v6, vcc, 0x1000, v6
	v_add_u32_e32 v4, 0x200, v4
	s_nop 0
	v_addc_co_u32_e32 v7, vcc, 0, v7, vcc
	global_load_dwordx4 v[56:59], v[6:7], off offset:512
	v_lshl_add_u32 v84, v5, 10, v12
	v_ashrrev_i32_e32 v5, 6, v4
	v_mov_b64_e32 v[6:7], s[24:25]
	v_add_u32_e32 v8, s8, v5
	v_lshlrev_b32_e32 v0, 1, v2
	v_mad_i64_i32 v[6:7], s[30:31], v8, s46, v[6:7]
	v_lshl_add_u64 v[6:7], v[6:7], 0, v[0:1]
	v_add_co_u32_e32 v6, vcc, 0x1000, v6
	v_add_u32_e32 v4, 0x200, v4
	s_nop 0
	v_addc_co_u32_e32 v7, vcc, 0, v7, vcc
	global_load_dwordx4 v[60:63], v[6:7], off offset:512
	v_lshl_add_u32 v85, v5, 10, v12
	v_ashrrev_i32_e32 v5, 6, v4
	v_mov_b64_e32 v[6:7], s[24:25]
	v_add_u32_e32 v8, s8, v5
	v_lshlrev_b32_e32 v0, 1, v2
	v_mad_i64_i32 v[6:7], s[30:31], v8, s46, v[6:7]
	v_lshl_add_u64 v[6:7], v[6:7], 0, v[0:1]
	v_add_co_u32_e32 v6, vcc, 0x1000, v6
	v_add_u32_e32 v4, 0x200, v4
	s_nop 0
	v_addc_co_u32_e32 v7, vcc, 0, v7, vcc
	global_load_dwordx4 v[64:67], v[6:7], off offset:512
	v_lshl_add_u32 v86, v5, 10, v12
	v_ashrrev_i32_e32 v5, 6, v4
	v_mov_b64_e32 v[6:7], s[24:25]
	v_add_u32_e32 v8, s8, v5
	v_lshlrev_b32_e32 v0, 1, v2
	v_mad_i64_i32 v[6:7], s[30:31], v8, s46, v[6:7]
	v_lshl_add_u64 v[6:7], v[6:7], 0, v[0:1]
	v_add_co_u32_e32 v6, vcc, 0x1000, v6
	v_add_u32_e32 v4, 0x200, v4
	s_nop 0
	v_addc_co_u32_e32 v7, vcc, 0, v7, vcc
	global_load_dwordx4 v[68:71], v[6:7], off offset:512
	v_lshl_add_u32 v87, v5, 10, v12
	v_ashrrev_i32_e32 v5, 6, v4
	v_mov_b64_e32 v[6:7], s[24:25]
	v_add_u32_e32 v8, s8, v5
	v_lshlrev_b32_e32 v0, 1, v2
	v_mad_i64_i32 v[6:7], s[30:31], v8, s46, v[6:7]
	v_lshl_add_u64 v[6:7], v[6:7], 0, v[0:1]
	v_add_co_u32_e32 v6, vcc, 0x1000, v6
	v_add_u32_e32 v4, 0x200, v4
	s_nop 0
	v_addc_co_u32_e32 v7, vcc, 0, v7, vcc
	global_load_dwordx4 v[72:75], v[6:7], off offset:512
	v_lshl_add_u32 v88, v5, 10, v12
	v_ashrrev_i32_e32 v5, 6, v4
	v_mov_b64_e32 v[6:7], s[24:25]
	v_add_u32_e32 v8, s8, v5
	v_lshlrev_b32_e32 v0, 1, v2
	v_mad_i64_i32 v[6:7], s[30:31], v8, s46, v[6:7]
	v_lshl_add_u64 v[6:7], v[6:7], 0, v[0:1]
	v_add_co_u32_e32 v6, vcc, 0x1000, v6
	v_add_u32_e32 v4, 0x200, v4
	s_nop 0
	v_addc_co_u32_e32 v7, vcc, 0, v7, vcc
	global_load_dwordx4 v[76:79], v[6:7], off offset:512
	v_lshl_add_u32 v89, v5, 10, v12
	s_waitcnt vmcnt(0)
	ds_write_b128 v80, v[40:43]
	ds_write_b128 v81, v[44:47]
	ds_write_b128 v82, v[48:51]
	ds_write_b128 v83, v[52:55]
	ds_write_b128 v84, v[56:59]
	ds_write_b128 v85, v[60:63]
	ds_write_b128 v86, v[64:67]
	ds_write_b128 v87, v[68:71]
	ds_write_b128 v88, v[72:75]
	ds_write_b128 v89, v[76:79]

; DEVI void ph_shw(const int wv, const Params& p, int l, unsigned char* lds, int blk_lo) {
;     ...
;         const float* w = p.in[19] + (size_t)l * 1024 * 4096 + n0 + n;
; #pragma unroll 8
;         for (int k = kg * 32; k < kg * 32 + 32; ++k) { const float wvv = w[(size_t)k * 4096];
; #pragma unroll
;             for (int r = 0; r < 17; ++r) acc[r] += shv[r * 1024 + k] * wvv; }
.LBB0_994:
	v_add_co_u32_e32 v120, vcc, s54, v80
	s_nop 1
	v_addc_co_u32_e32 v121, vcc, -1, v81, vcc
	global_load_dword v110, v[120:121], off
	v_add_co_u32_e32 v120, vcc, s56, v80
	s_nop 1
	v_addc_co_u32_e32 v121, vcc, -1, v81, vcc
	global_load_dword v111, v[120:121], off
	v_add_co_u32_e32 v120, vcc, s57, v80
	s_nop 1
	v_addc_co_u32_e32 v121, vcc, -1, v81, vcc
	global_load_dword v112, v[120:121], off
	v_add_co_u32_e32 v120, vcc, s52, v80
	s_nop 1
	v_addc_co_u32_e32 v121, vcc, -1, v81, vcc
	global_load_dword v113, v[120:121], off
	v_add_co_u32_e32 v120, vcc, s58, v80
	s_nop 1
	v_addc_co_u32_e32 v121, vcc, -1, v81, vcc
	global_load_dword v114, v[120:121], off
	v_add_co_u32_e32 v120, vcc, s51, v80
	s_nop 1
	v_addc_co_u32_e32 v121, vcc, -1, v81, vcc
	global_load_dword v115, v[120:121], off
	v_add_co_u32_e32 v120, vcc, s59, v80
	s_nop 1
	v_addc_co_u32_e32 v121, vcc, -1, v81, vcc
	global_load_dword v116, v[120:121], off
	global_load_dword v117, v[80:81], off
	v_add_co_u32_e32 v2, vcc, s54, v80
	v_add_u32_e32 v104, s13, v102
	s_nop 0
	v_addc_co_u32_e32 v3, vcc, -1, v81, vcc
	s_waitcnt vmcnt(0)
	v_mov_b32_e32 v106, v110
	ds_read_b128 v[6:9], v104
	ds_read_b128 v[2:5], v104 offset:16
	ds_read_b128 v[10:13], v104 offset:4096
	s_add_i32 s13, s13, 32
	s_cmpk_eq_i32 s13, 0x80
	s_waitcnt lgkmcnt(2)
	v_mov_b32_e32 v16, v6
	v_add_u32_e32 v6, 0x10000, v104
	s_waitcnt lgkmcnt(0)
	v_mov_b32_e32 v17, v10
	v_mov_b32_e32 v10, v7
	s_waitcnt vmcnt(0)
	v_pk_fma_f32 v[82:83], v[106:107], v[16:17], v[14:15] op_sel_hi:[0,1,1]
	ds_read_b128 v[14:17], v104 offset:8192
	ds_read_b128 v[18:21], v104 offset:12288
	s_waitcnt lgkmcnt(1)
	v_mov_b32_e32 v24, v14
	s_waitcnt lgkmcnt(0)
	v_mov_b32_e32 v25, v18
	v_pk_fma_f32 v[84:85], v[106:107], v[24:25], v[22:23] op_sel_hi:[0,1,1]
	ds_read_b128 v[22:25], v104 offset:16384
	ds_read_b128 v[26:29], v104 offset:20480
	v_mov_b32_e32 v18, v15
	s_waitcnt lgkmcnt(1)
	v_mov_b32_e32 v32, v22
	s_waitcnt lgkmcnt(0)
	v_mov_b32_e32 v33, v26
	v_pk_fma_f32 v[86:87], v[106:107], v[32:33], v[30:31] op_sel_hi:[0,1,1]
	ds_read_b128 v[30:33], v104 offset:24576
	ds_read_b128 v[34:37], v104 offset:28672
	v_mov_b32_e32 v26, v23
	s_waitcnt lgkmcnt(1)
	v_mov_b32_e32 v40, v30
	s_waitcnt lgkmcnt(0)
	v_mov_b32_e32 v41, v34
	v_pk_fma_f32 v[88:89], v[106:107], v[40:41], v[38:39] op_sel_hi:[0,1,1]
	ds_read_b128 v[38:41], v104 offset:32768
	ds_read_b128 v[42:45], v104 offset:36864
	v_mov_b32_e32 v34, v31
	s_waitcnt lgkmcnt(1)
	v_mov_b32_e32 v48, v38
	s_waitcnt lgkmcnt(0)
	v_mov_b32_e32 v49, v42
	v_pk_fma_f32 v[90:91], v[106:107], v[48:49], v[46:47] op_sel_hi:[0,1,1]
	ds_read_b128 v[46:49], v104 offset:40960
	ds_read_b128 v[50:53], v104 offset:45056
	v_mov_b32_e32 v42, v39
	s_waitcnt lgkmcnt(1)
	v_mov_b32_e32 v56, v46
	s_waitcnt lgkmcnt(0)
	v_mov_b32_e32 v57, v50
	v_pk_fma_f32 v[92:93], v[106:107], v[56:57], v[54:55] op_sel_hi:[0,1,1]
	ds_read_b128 v[54:57], v104 offset:49152
	ds_read_b128 v[58:61], v104 offset:53248
	v_mov_b32_e32 v50, v47
	s_waitcnt lgkmcnt(1)
	v_mov_b32_e32 v64, v54
	s_waitcnt lgkmcnt(0)
	v_mov_b32_e32 v65, v58
	v_pk_fma_f32 v[94:95], v[106:107], v[64:65], v[62:63] op_sel_hi:[0,1,1]
	ds_read_b128 v[62:65], v104 offset:57344
	ds_read_b128 v[66:69], v104 offset:61440
	v_mov_b32_e32 v58, v55
	s_waitcnt lgkmcnt(1)
	v_mov_b32_e32 v72, v62
	s_waitcnt lgkmcnt(0)
	v_mov_b32_e32 v73, v66
	v_pk_fma_f32 v[108:109], v[106:107], v[72:73], v[70:71] op_sel_hi:[0,1,1]
	ds_read_b128 v[70:73], v6
	v_mov_b32_e32 v66, v63
	s_waitcnt lgkmcnt(0)
	v_fmac_f32_e32 v0, v106, v70
	v_add_co_u32_e32 v106, vcc, s56, v80
	s_nop 1
	v_addc_co_u32_e32 v107, vcc, -1, v81, vcc
	s_waitcnt vmcnt(0)
	v_mov_b32_e32 v6, v111
	s_waitcnt vmcnt(0)
	v_pk_fma_f32 v[10:11], v[6:7], v[10:11], v[82:83] op_sel_hi:[0,1,1]
	v_pk_fma_f32 v[14:15], v[6:7], v[18:19], v[84:85] op_sel_hi:[0,1,1]
	v_pk_fma_f32 v[18:19], v[6:7], v[26:27], v[86:87] op_sel_hi:[0,1,1]
	v_pk_fma_f32 v[22:23], v[6:7], v[34:35], v[88:89] op_sel_hi:[0,1,1]
	v_pk_fma_f32 v[26:27], v[6:7], v[42:43], v[90:91] op_sel_hi:[0,1,1]
	v_pk_fma_f32 v[30:31], v[6:7], v[50:51], v[92:93] op_sel_hi:[0,1,1]
	v_pk_fma_f32 v[34:35], v[6:7], v[58:59], v[94:95] op_sel_hi:[0,1,1]
	v_pk_fma_f32 v[38:39], v[6:7], v[66:67], v[108:109] op_sel_hi:[0,1,1]
	v_fmac_f32_e32 v0, v6, v71
	v_add_co_u32_e32 v6, vcc, s57, v80
	v_mov_b32_e32 v42, v8
	s_nop 0
	v_addc_co_u32_e32 v7, vcc, -1, v81, vcc
	s_waitcnt vmcnt(0)
	v_mov_b32_e32 v6, v112
	v_mov_b32_e32 v43, v12
	v_mov_b32_e32 v12, v9
	s_waitcnt vmcnt(0)
	v_pk_fma_f32 v[10:11], v[6:7], v[42:43], v[10:11] op_sel_hi:[0,1,1]
	v_mov_b32_e32 v42, v16
	v_mov_b32_e32 v43, v20
	v_pk_fma_f32 v[14:15], v[6:7], v[42:43], v[14:15] op_sel_hi:[0,1,1]
	v_mov_b32_e32 v42, v24
	v_mov_b32_e32 v43, v28
	v_pk_fma_f32 v[18:19], v[6:7], v[42:43], v[18:19] op_sel_hi:[0,1,1]
	v_mov_b32_e32 v42, v32
	v_mov_b32_e32 v43, v36
	v_pk_fma_f32 v[22:23], v[6:7], v[42:43], v[22:23] op_sel_hi:[0,1,1]
	v_mov_b32_e32 v42, v40
	v_mov_b32_e32 v43, v44
	v_pk_fma_f32 v[26:27], v[6:7], v[42:43], v[26:27] op_sel_hi:[0,1,1]
	v_mov_b32_e32 v42, v48
	v_mov_b32_e32 v43, v52
	v_pk_fma_f32 v[30:31], v[6:7], v[42:43], v[30:31] op_sel_hi:[0,1,1]
	v_mov_b32_e32 v42, v56
	v_mov_b32_e32 v43, v60
	v_pk_fma_f32 v[34:35], v[6:7], v[42:43], v[34:35] op_sel_hi:[0,1,1]
	v_mov_b32_e32 v42, v64
	v_mov_b32_e32 v43, v68
	v_pk_fma_f32 v[38:39], v[6:7], v[42:43], v[38:39] op_sel_hi:[0,1,1]
	v_fmac_f32_e32 v0, v6, v72
	v_add_co_u32_e32 v6, vcc, s52, v80
	v_mov_b32_e32 v20, v17
	s_nop 0
	v_addc_co_u32_e32 v7, vcc, -1, v81, vcc
	s_waitcnt vmcnt(0)
	v_mov_b32_e32 v6, v113
	v_mov_b32_e32 v28, v25
	v_mov_b32_e32 v36, v33
	v_mov_b32_e32 v44, v41
	v_mov_b32_e32 v52, v49
	v_mov_b32_e32 v60, v57
	v_mov_b32_e32 v68, v65
	s_waitcnt vmcnt(0)
; DEVI void ph_shw(const int wv, const Params& p, int l, unsigned char* lds, int blk_lo) {
;     ...
;         for (int k = kg * 32; k < kg * 32 + 32; ++k) { const float wvv = w[(size_t)k * 4096];
; #pragma unroll
;             for (int r = 0; r < 17; ++r) acc[r] += shv[r * 1024 + k] * wvv; }
; #pragma unroll
;         for (int r = 0; r < 17; ++r) red[(kg * 17 + r) * 16 + n] = acc[r];
;         __syncthreads();
;         for (int e = tid; e < 17 * 16; e += NTHREADS) { const int r = e >> 4, nn = e & 15; float sacc = 0.f;
; #pragma unroll
;             for (int q = 0; q < 32; ++q) sacc += red[(q * 17 + r) * 16 + nn];
;             ((float*)(p.ws + OFF_SHW2))[(size_t)(l * 17 + r) * 4096 + n0 + nn] = sacc; }
	v_pk_fma_f32 v[10:11], v[6:7], v[12:13], v[10:11] op_sel_hi:[0,1,1]
	v_pk_fma_f32 v[20:21], v[6:7], v[20:21], v[14:15] op_sel_hi:[0,1,1]
	v_pk_fma_f32 v[28:29], v[6:7], v[28:29], v[18:19] op_sel_hi:[0,1,1]
	v_pk_fma_f32 v[36:37], v[6:7], v[36:37], v[22:23] op_sel_hi:[0,1,1]
	v_pk_fma_f32 v[42:43], v[6:7], v[44:45], v[26:27] op_sel_hi:[0,1,1]
	v_pk_fma_f32 v[50:51], v[6:7], v[52:53], v[30:31] op_sel_hi:[0,1,1]
	v_pk_fma_f32 v[58:59], v[6:7], v[60:61], v[34:35] op_sel_hi:[0,1,1]
	v_pk_fma_f32 v[66:67], v[6:7], v[68:69], v[38:39] op_sel_hi:[0,1,1]
	v_fmac_f32_e32 v0, v6, v73
	v_add_co_u32_e32 v6, vcc, s58, v80
	v_mov_b32_e32 v12, v2
	s_nop 0
	v_addc_co_u32_e32 v7, vcc, -1, v81, vcc
	s_waitcnt vmcnt(0)
	v_mov_b32_e32 v72, v114
	ds_read_b128 v[6:9], v104 offset:4112
	v_add_u32_e32 v2, 0x10010, v104
	s_waitcnt lgkmcnt(0)
	v_mov_b32_e32 v13, v6
	v_mov_b32_e32 v6, v3
	s_waitcnt vmcnt(0)
	v_pk_fma_f32 v[70:71], v[72:73], v[12:13], v[10:11] op_sel_hi:[0,1,1]
	ds_read_b128 v[10:13], v104 offset:8208
	ds_read_b128 v[14:17], v104 offset:12304
	s_waitcnt lgkmcnt(1)
	v_mov_b32_e32 v18, v10
	s_waitcnt lgkmcnt(0)
	v_mov_b32_e32 v19, v14
	v_pk_fma_f32 v[82:83], v[72:73], v[18:19], v[20:21] op_sel_hi:[0,1,1]
	ds_read_b128 v[18:21], v104 offset:16400
	ds_read_b128 v[22:25], v104 offset:20496
	v_mov_b32_e32 v14, v11
	s_waitcnt lgkmcnt(1)
	v_mov_b32_e32 v26, v18
	s_waitcnt lgkmcnt(0)
	v_mov_b32_e32 v27, v22
	v_pk_fma_f32 v[84:85], v[72:73], v[26:27], v[28:29] op_sel_hi:[0,1,1]
	ds_read_b128 v[26:29], v104 offset:24592
	ds_read_b128 v[30:33], v104 offset:28688
	v_mov_b32_e32 v22, v19
	s_waitcnt lgkmcnt(1)
	v_mov_b32_e32 v34, v26
	s_waitcnt lgkmcnt(0)
	v_mov_b32_e32 v35, v30
	v_pk_fma_f32 v[86:87], v[72:73], v[34:35], v[36:37] op_sel_hi:[0,1,1]
	ds_read_b128 v[34:37], v104 offset:32784
	ds_read_b128 v[38:41], v104 offset:36880
	v_mov_b32_e32 v30, v27
	s_waitcnt lgkmcnt(1)
	v_mov_b32_e32 v44, v34
	s_waitcnt lgkmcnt(0)
	v_mov_b32_e32 v45, v38
	v_pk_fma_f32 v[88:89], v[72:73], v[44:45], v[42:43] op_sel_hi:[0,1,1]
	ds_read_b128 v[42:45], v104 offset:40976
	ds_read_b128 v[46:49], v104 offset:45072
	v_mov_b32_e32 v38, v35
	s_waitcnt lgkmcnt(1)
	v_mov_b32_e32 v52, v42
	s_waitcnt lgkmcnt(0)
	v_mov_b32_e32 v53, v46
	v_pk_fma_f32 v[90:91], v[72:73], v[52:53], v[50:51] op_sel_hi:[0,1,1]
	ds_read_b128 v[50:53], v104 offset:49168
	ds_read_b128 v[54:57], v104 offset:53264
	v_mov_b32_e32 v46, v43
	s_waitcnt lgkmcnt(1)
	v_mov_b32_e32 v60, v50
	s_waitcnt lgkmcnt(0)
	v_mov_b32_e32 v61, v54
	v_pk_fma_f32 v[92:93], v[72:73], v[60:61], v[58:59] op_sel_hi:[0,1,1]
	ds_read_b128 v[58:61], v104 offset:57360
	ds_read_b128 v[62:65], v104 offset:61456
	v_mov_b32_e32 v54, v51
	s_waitcnt lgkmcnt(1)
	v_mov_b32_e32 v68, v58
	s_waitcnt lgkmcnt(0)
	v_mov_b32_e32 v69, v62
	v_pk_fma_f32 v[94:95], v[72:73], v[68:69], v[66:67] op_sel_hi:[0,1,1]
	ds_read_b128 v[66:69], v2
	v_mov_b32_e32 v62, v59
	s_waitcnt lgkmcnt(0)
	v_fmac_f32_e32 v0, v72, v66
	v_add_co_u32_e32 v72, vcc, s51, v80
	s_nop 1
	v_addc_co_u32_e32 v73, vcc, -1, v81, vcc
	s_waitcnt vmcnt(0)
	v_mov_b32_e32 v2, v115
	s_waitcnt vmcnt(0)
	v_pk_fma_f32 v[6:7], v[2:3], v[6:7], v[70:71] op_sel_hi:[0,1,1]
	v_pk_fma_f32 v[10:11], v[2:3], v[14:15], v[82:83] op_sel_hi:[0,1,1]
	v_pk_fma_f32 v[14:15], v[2:3], v[22:23], v[84:85] op_sel_hi:[0,1,1]
	v_pk_fma_f32 v[18:19], v[2:3], v[30:31], v[86:87] op_sel_hi:[0,1,1]
	v_pk_fma_f32 v[22:23], v[2:3], v[38:39], v[88:89] op_sel_hi:[0,1,1]
	v_pk_fma_f32 v[26:27], v[2:3], v[46:47], v[90:91] op_sel_hi:[0,1,1]
	v_pk_fma_f32 v[30:31], v[2:3], v[54:55], v[92:93] op_sel_hi:[0,1,1]
	v_pk_fma_f32 v[34:35], v[2:3], v[62:63], v[94:95] op_sel_hi:[0,1,1]
	v_fmac_f32_e32 v0, v2, v67
	v_add_co_u32_e32 v2, vcc, s59, v80
	v_mov_b32_e32 v38, v4
	s_nop 0
	v_addc_co_u32_e32 v3, vcc, -1, v81, vcc
	s_waitcnt vmcnt(0)
	v_mov_b32_e32 v2, v116
	v_mov_b32_e32 v39, v8
	v_mov_b32_e32 v8, v5
	s_waitcnt vmcnt(0)
	v_pk_fma_f32 v[6:7], v[2:3], v[38:39], v[6:7] op_sel_hi:[0,1,1]
	v_mov_b32_e32 v38, v12
	v_mov_b32_e32 v39, v16
	v_pk_fma_f32 v[10:11], v[2:3], v[38:39], v[10:11] op_sel_hi:[0,1,1]
	v_mov_b32_e32 v38, v20
	v_mov_b32_e32 v39, v24
	v_pk_fma_f32 v[38:39], v[2:3], v[38:39], v[14:15] op_sel_hi:[0,1,1]
	v_mov_b32_e32 v14, v28
	v_mov_b32_e32 v15, v32
	v_pk_fma_f32 v[18:19], v[2:3], v[14:15], v[18:19] op_sel_hi:[0,1,1]
	v_mov_b32_e32 v14, v36
	v_mov_b32_e32 v15, v40
	v_pk_fma_f32 v[42:43], v[2:3], v[14:15], v[22:23] op_sel_hi:[0,1,1]
	v_mov_b32_e32 v14, v44
	v_mov_b32_e32 v15, v48
	v_pk_fma_f32 v[26:27], v[2:3], v[14:15], v[26:27] op_sel_hi:[0,1,1]
	v_mov_b32_e32 v14, v52
	v_mov_b32_e32 v15, v56
	v_pk_fma_f32 v[50:51], v[2:3], v[14:15], v[30:31] op_sel_hi:[0,1,1]
	v_mov_b32_e32 v14, v60
	v_mov_b32_e32 v15, v64
	v_pk_fma_f32 v[34:35], v[2:3], v[14:15], v[34:35] op_sel_hi:[0,1,1]
	v_fmac_f32_e32 v0, v2, v68
	s_waitcnt vmcnt(0)
	v_mov_b32_e32 v2, v117
	v_mov_b32_e32 v16, v13
	v_mov_b32_e32 v24, v21
	v_mov_b32_e32 v32, v29
	v_mov_b32_e32 v40, v37
	v_mov_b32_e32 v48, v45
	v_mov_b32_e32 v56, v53
	v_mov_b32_e32 v64, v61
	v_lshl_add_u64 v[80:81], v[80:81], 0, s[28:29]
	s_waitcnt vmcnt(0)
	v_pk_fma_f32 v[14:15], v[2:3], v[8:9], v[6:7] op_sel_hi:[0,1,1]
	v_pk_fma_f32 v[22:23], v[2:3], v[16:17], v[10:11] op_sel_hi:[0,1,1]
	v_pk_fma_f32 v[30:31], v[2:3], v[24:25], v[38:39] op_sel_hi:[0,1,1]
	v_pk_fma_f32 v[38:39], v[2:3], v[32:33], v[18:19] op_sel_hi:[0,1,1]
	v_pk_fma_f32 v[46:47], v[2:3], v[40:41], v[42:43] op_sel_hi:[0,1,1]
	v_pk_fma_f32 v[54:55], v[2:3], v[48:49], v[26:27] op_sel_hi:[0,1,1]
	v_pk_fma_f32 v[62:63], v[2:3], v[56:57], v[50:51] op_sel_hi:[0,1,1]
	v_pk_fma_f32 v[70:71], v[2:3], v[64:65], v[34:35] op_sel_hi:[0,1,1]
	v_fmac_f32_e32 v0, v2, v69
	s_cbranch_scc0 .LBB0_994
	ds_write2_b32 v103, v14, v15 offset1:16
	ds_write2_b32 v103, v22, v23 offset0:32 offset1:48
	ds_write2_b32 v103, v30, v31 offset0:64 offset1:80
	ds_write2_b32 v103, v38, v39 offset0:96 offset1:112
	ds_write2_b32 v103, v46, v47 offset0:128 offset1:144
	ds_write2_b32 v103, v54, v55 offset0:160 offset1:176
	ds_write2_b32 v103, v62, v63 offset0:192 offset1:208
	ds_write2_b32 v103, v70, v71 offset0:224 offset1:240
	ds_write_b32 v103, v0 offset:1024
	s_waitcnt lgkmcnt(0)
	s_barrier
	s_and_saveexec_b64 s[28:29], s[2:3]
	s_cbranch_execz .LBB0_984
	s_lshl_b32 s30, s18, 4
	s_ashr_i32 s31, s30, 31
	v_lshl_add_u64 v[2:3], s[30:31], 2, v[76:77]
	s_mov_b64 s[36:37], -1
	v_mov_b32_e32 v0, v74
	s_and_saveexec_b64 s[30:31], s[8:9]
	s_cbranch_execz .LBB0_1000
	s_mov_b64 s[36:37], 0
	v_mov_b32_e32 v0, v99
	v_mov_b64_e32 v[4:5], v[74:75]

; DEVI void ph_shw(const int wv, const Params& p, int l, unsigned char* lds, int blk_lo) {
;     ...
;         const float* w = p.in[19] + (size_t)l * 1024 * 4096 + n0 + n;
; #pragma unroll 8
;         for (int k = kg * 32; k < kg * 32 + 32; ++k) { const float wvv = w[(size_t)k * 4096];
; #pragma unroll
;             for (int r = 0; r < 17; ++r) acc[r] += shv[r * 1024 + k] * wvv; }
.LBB0_1207:
	v_add_co_u32_e32 v120, vcc, s52, v80
	s_nop 1
	v_addc_co_u32_e32 v121, vcc, -1, v81, vcc
	global_load_dword v110, v[120:121], off
	v_add_co_u32_e32 v120, vcc, s53, v80
	s_nop 1
	v_addc_co_u32_e32 v121, vcc, -1, v81, vcc
	global_load_dword v111, v[120:121], off
	v_add_co_u32_e32 v120, vcc, s54, v80
	s_nop 1
	v_addc_co_u32_e32 v121, vcc, -1, v81, vcc
	global_load_dword v112, v[120:121], off
	v_add_co_u32_e32 v120, vcc, s41, v80
	s_nop 1
	v_addc_co_u32_e32 v121, vcc, -1, v81, vcc
	global_load_dword v113, v[120:121], off
	v_add_co_u32_e32 v120, vcc, s56, v80
	s_nop 1
	v_addc_co_u32_e32 v121, vcc, -1, v81, vcc
	global_load_dword v114, v[120:121], off
	v_add_co_u32_e32 v120, vcc, s40, v80
	s_nop 1
	v_addc_co_u32_e32 v121, vcc, -1, v81, vcc
	global_load_dword v115, v[120:121], off
	v_add_co_u32_e32 v120, vcc, s57, v80
	s_nop 1
	v_addc_co_u32_e32 v121, vcc, -1, v81, vcc
	global_load_dword v116, v[120:121], off
	global_load_dword v117, v[80:81], off
	v_add_co_u32_e32 v2, vcc, s52, v80
	v_add_u32_e32 v104, s13, v102
	s_nop 0
	v_addc_co_u32_e32 v3, vcc, -1, v81, vcc
	s_waitcnt vmcnt(0)
	v_mov_b32_e32 v106, v110
	ds_read_b128 v[6:9], v104
	ds_read_b128 v[2:5], v104 offset:16
	ds_read_b128 v[10:13], v104 offset:4096
	s_add_i32 s13, s13, 32
	s_cmpk_eq_i32 s13, 0x80
	s_waitcnt lgkmcnt(2)
	v_mov_b32_e32 v16, v6
	v_add_u32_e32 v6, 0x10000, v104
	s_waitcnt lgkmcnt(0)
	v_mov_b32_e32 v17, v10
	v_mov_b32_e32 v10, v7
	s_waitcnt vmcnt(0)
	v_pk_fma_f32 v[82:83], v[106:107], v[16:17], v[14:15] op_sel_hi:[0,1,1]
	ds_read_b128 v[14:17], v104 offset:8192
	ds_read_b128 v[18:21], v104 offset:12288
	s_waitcnt lgkmcnt(1)
	v_mov_b32_e32 v24, v14
	s_waitcnt lgkmcnt(0)
	v_mov_b32_e32 v25, v18
	v_pk_fma_f32 v[84:85], v[106:107], v[24:25], v[22:23] op_sel_hi:[0,1,1]
	ds_read_b128 v[22:25], v104 offset:16384
	ds_read_b128 v[26:29], v104 offset:20480
	v_mov_b32_e32 v18, v15
	s_waitcnt lgkmcnt(1)
	v_mov_b32_e32 v32, v22
	s_waitcnt lgkmcnt(0)
	v_mov_b32_e32 v33, v26
	v_pk_fma_f32 v[86:87], v[106:107], v[32:33], v[30:31] op_sel_hi:[0,1,1]
	ds_read_b128 v[30:33], v104 offset:24576
	ds_read_b128 v[34:37], v104 offset:28672
	v_mov_b32_e32 v26, v23
	s_waitcnt lgkmcnt(1)
	v_mov_b32_e32 v40, v30
	s_waitcnt lgkmcnt(0)
	v_mov_b32_e32 v41, v34
	v_pk_fma_f32 v[88:89], v[106:107], v[40:41], v[38:39] op_sel_hi:[0,1,1]
	ds_read_b128 v[38:41], v104 offset:32768
	ds_read_b128 v[42:45], v104 offset:36864
	v_mov_b32_e32 v34, v31
	s_waitcnt lgkmcnt(1)
	v_mov_b32_e32 v48, v38
	s_waitcnt lgkmcnt(0)
	v_mov_b32_e32 v49, v42
	v_pk_fma_f32 v[90:91], v[106:107], v[48:49], v[46:47] op_sel_hi:[0,1,1]
	ds_read_b128 v[46:49], v104 offset:40960
	ds_read_b128 v[50:53], v104 offset:45056
	v_mov_b32_e32 v42, v39
	s_waitcnt lgkmcnt(1)
	v_mov_b32_e32 v56, v46
	s_waitcnt lgkmcnt(0)
	v_mov_b32_e32 v57, v50
	v_pk_fma_f32 v[92:93], v[106:107], v[56:57], v[54:55] op_sel_hi:[0,1,1]
	ds_read_b128 v[54:57], v104 offset:49152
	ds_read_b128 v[58:61], v104 offset:53248
	v_mov_b32_e32 v50, v47
	s_waitcnt lgkmcnt(1)
	v_mov_b32_e32 v64, v54
	s_waitcnt lgkmcnt(0)
	v_mov_b32_e32 v65, v58
	v_pk_fma_f32 v[94:95], v[106:107], v[64:65], v[62:63] op_sel_hi:[0,1,1]
	ds_read_b128 v[62:65], v104 offset:57344
	ds_read_b128 v[66:69], v104 offset:61440
	v_mov_b32_e32 v58, v55
	s_waitcnt lgkmcnt(1)
	v_mov_b32_e32 v72, v62
	s_waitcnt lgkmcnt(0)
	v_mov_b32_e32 v73, v66
	v_pk_fma_f32 v[108:109], v[106:107], v[72:73], v[70:71] op_sel_hi:[0,1,1]
	ds_read_b128 v[70:73], v6
	v_mov_b32_e32 v66, v63
	s_waitcnt lgkmcnt(0)
	v_fmac_f32_e32 v0, v106, v70
	v_add_co_u32_e32 v106, vcc, s53, v80
	s_nop 1
	v_addc_co_u32_e32 v107, vcc, -1, v81, vcc
	s_waitcnt vmcnt(0)
	v_mov_b32_e32 v6, v111
	s_waitcnt vmcnt(0)
	v_pk_fma_f32 v[10:11], v[6:7], v[10:11], v[82:83] op_sel_hi:[0,1,1]
	v_pk_fma_f32 v[14:15], v[6:7], v[18:19], v[84:85] op_sel_hi:[0,1,1]
	v_pk_fma_f32 v[18:19], v[6:7], v[26:27], v[86:87] op_sel_hi:[0,1,1]
	v_pk_fma_f32 v[22:23], v[6:7], v[34:35], v[88:89] op_sel_hi:[0,1,1]
	v_pk_fma_f32 v[26:27], v[6:7], v[42:43], v[90:91] op_sel_hi:[0,1,1]
	v_pk_fma_f32 v[30:31], v[6:7], v[50:51], v[92:93] op_sel_hi:[0,1,1]
	v_pk_fma_f32 v[34:35], v[6:7], v[58:59], v[94:95] op_sel_hi:[0,1,1]
	v_pk_fma_f32 v[38:39], v[6:7], v[66:67], v[108:109] op_sel_hi:[0,1,1]
	v_fmac_f32_e32 v0, v6, v71
	v_add_co_u32_e32 v6, vcc, s54, v80
	v_mov_b32_e32 v42, v8
	s_nop 0
	v_addc_co_u32_e32 v7, vcc, -1, v81, vcc
	s_waitcnt vmcnt(0)
	v_mov_b32_e32 v6, v112
	v_mov_b32_e32 v43, v12
	v_mov_b32_e32 v12, v9
	s_waitcnt vmcnt(0)
	v_pk_fma_f32 v[10:11], v[6:7], v[42:43], v[10:11] op_sel_hi:[0,1,1]
	v_mov_b32_e32 v42, v16
	v_mov_b32_e32 v43, v20
	v_pk_fma_f32 v[14:15], v[6:7], v[42:43], v[14:15] op_sel_hi:[0,1,1]
	v_mov_b32_e32 v42, v24
	v_mov_b32_e32 v43, v28
	v_pk_fma_f32 v[18:19], v[6:7], v[42:43], v[18:19] op_sel_hi:[0,1,1]
	v_mov_b32_e32 v42, v32
	v_mov_b32_e32 v43, v36
	v_pk_fma_f32 v[22:23], v[6:7], v[42:43], v[22:23] op_sel_hi:[0,1,1]
	v_mov_b32_e32 v42, v40
	v_mov_b32_e32 v43, v44
	v_pk_fma_f32 v[26:27], v[6:7], v[42:43], v[26:27] op_sel_hi:[0,1,1]
	v_mov_b32_e32 v42, v48
	v_mov_b32_e32 v43, v52
	v_pk_fma_f32 v[30:31], v[6:7], v[42:43], v[30:31] op_sel_hi:[0,1,1]
	v_mov_b32_e32 v42, v56
	v_mov_b32_e32 v43, v60
	v_pk_fma_f32 v[34:35], v[6:7], v[42:43], v[34:35] op_sel_hi:[0,1,1]
	v_mov_b32_e32 v42, v64
	v_mov_b32_e32 v43, v68
	v_pk_fma_f32 v[38:39], v[6:7], v[42:43], v[38:39] op_sel_hi:[0,1,1]
	v_fmac_f32_e32 v0, v6, v72
	v_add_co_u32_e32 v6, vcc, s41, v80
	v_mov_b32_e32 v20, v17
	s_nop 0
	v_addc_co_u32_e32 v7, vcc, -1, v81, vcc
	s_waitcnt vmcnt(0)
	v_mov_b32_e32 v6, v113
	v_mov_b32_e32 v28, v25
	v_mov_b32_e32 v36, v33
	v_mov_b32_e32 v44, v41
	v_mov_b32_e32 v52, v49
	v_mov_b32_e32 v60, v57
	v_mov_b32_e32 v68, v65
	s_waitcnt vmcnt(0)
; DEVI void ph_shw(const int wv, const Params& p, int l, unsigned char* lds, int blk_lo) {
;     ...
;         for (int k = kg * 32; k < kg * 32 + 32; ++k) { const float wvv = w[(size_t)k * 4096];
; #pragma unroll
;             for (int r = 0; r < 17; ++r) acc[r] += shv[r * 1024 + k] * wvv; }
; #pragma unroll
;         for (int r = 0; r < 17; ++r) red[(kg * 17 + r) * 16 + n] = acc[r];
;         __syncthreads();
;         for (int e = tid; e < 17 * 16; e += NTHREADS) { const int r = e >> 4, nn = e & 15; float sacc = 0.f;
; #pragma unroll
;             for (int q = 0; q < 32; ++q) sacc += red[(q * 17 + r) * 16 + nn];
;             ((float*)(p.ws + OFF_SHW2))[(size_t)(l * 17 + r) * 4096 + n0 + nn] = sacc; }
	v_pk_fma_f32 v[10:11], v[6:7], v[12:13], v[10:11] op_sel_hi:[0,1,1]
	v_pk_fma_f32 v[20:21], v[6:7], v[20:21], v[14:15] op_sel_hi:[0,1,1]
	v_pk_fma_f32 v[28:29], v[6:7], v[28:29], v[18:19] op_sel_hi:[0,1,1]
	v_pk_fma_f32 v[36:37], v[6:7], v[36:37], v[22:23] op_sel_hi:[0,1,1]
	v_pk_fma_f32 v[42:43], v[6:7], v[44:45], v[26:27] op_sel_hi:[0,1,1]
	v_pk_fma_f32 v[50:51], v[6:7], v[52:53], v[30:31] op_sel_hi:[0,1,1]
	v_pk_fma_f32 v[58:59], v[6:7], v[60:61], v[34:35] op_sel_hi:[0,1,1]
	v_pk_fma_f32 v[66:67], v[6:7], v[68:69], v[38:39] op_sel_hi:[0,1,1]
	v_fmac_f32_e32 v0, v6, v73
	v_add_co_u32_e32 v6, vcc, s56, v80
	v_mov_b32_e32 v12, v2
	s_nop 0
	v_addc_co_u32_e32 v7, vcc, -1, v81, vcc
	s_waitcnt vmcnt(0)
	v_mov_b32_e32 v72, v114
	ds_read_b128 v[6:9], v104 offset:4112
	v_add_u32_e32 v2, 0x10010, v104
	s_waitcnt lgkmcnt(0)
	v_mov_b32_e32 v13, v6
	v_mov_b32_e32 v6, v3
	s_waitcnt vmcnt(0)
	v_pk_fma_f32 v[70:71], v[72:73], v[12:13], v[10:11] op_sel_hi:[0,1,1]
	ds_read_b128 v[10:13], v104 offset:8208
	ds_read_b128 v[14:17], v104 offset:12304
	s_waitcnt lgkmcnt(1)
	v_mov_b32_e32 v18, v10
	s_waitcnt lgkmcnt(0)
	v_mov_b32_e32 v19, v14
	v_pk_fma_f32 v[82:83], v[72:73], v[18:19], v[20:21] op_sel_hi:[0,1,1]
	ds_read_b128 v[18:21], v104 offset:16400
	ds_read_b128 v[22:25], v104 offset:20496
	v_mov_b32_e32 v14, v11
	s_waitcnt lgkmcnt(1)
	v_mov_b32_e32 v26, v18
	s_waitcnt lgkmcnt(0)
	v_mov_b32_e32 v27, v22
	v_pk_fma_f32 v[84:85], v[72:73], v[26:27], v[28:29] op_sel_hi:[0,1,1]
	ds_read_b128 v[26:29], v104 offset:24592
	ds_read_b128 v[30:33], v104 offset:28688
	v_mov_b32_e32 v22, v19
	s_waitcnt lgkmcnt(1)
	v_mov_b32_e32 v34, v26
	s_waitcnt lgkmcnt(0)
	v_mov_b32_e32 v35, v30
	v_pk_fma_f32 v[86:87], v[72:73], v[34:35], v[36:37] op_sel_hi:[0,1,1]
	ds_read_b128 v[34:37], v104 offset:32784
	ds_read_b128 v[38:41], v104 offset:36880
	v_mov_b32_e32 v30, v27
	s_waitcnt lgkmcnt(1)
	v_mov_b32_e32 v44, v34
	s_waitcnt lgkmcnt(0)
	v_mov_b32_e32 v45, v38
	v_pk_fma_f32 v[88:89], v[72:73], v[44:45], v[42:43] op_sel_hi:[0,1,1]
	ds_read_b128 v[42:45], v104 offset:40976
	ds_read_b128 v[46:49], v104 offset:45072
	v_mov_b32_e32 v38, v35
	s_waitcnt lgkmcnt(1)
	v_mov_b32_e32 v52, v42
	s_waitcnt lgkmcnt(0)
	v_mov_b32_e32 v53, v46
	v_pk_fma_f32 v[90:91], v[72:73], v[52:53], v[50:51] op_sel_hi:[0,1,1]
	ds_read_b128 v[50:53], v104 offset:49168
	ds_read_b128 v[54:57], v104 offset:53264
	v_mov_b32_e32 v46, v43
	s_waitcnt lgkmcnt(1)
	v_mov_b32_e32 v60, v50
	s_waitcnt lgkmcnt(0)
	v_mov_b32_e32 v61, v54
	v_pk_fma_f32 v[92:93], v[72:73], v[60:61], v[58:59] op_sel_hi:[0,1,1]
	ds_read_b128 v[58:61], v104 offset:57360
	ds_read_b128 v[62:65], v104 offset:61456
	v_mov_b32_e32 v54, v51
	s_waitcnt lgkmcnt(1)
	v_mov_b32_e32 v68, v58
	s_waitcnt lgkmcnt(0)
	v_mov_b32_e32 v69, v62
	v_pk_fma_f32 v[94:95], v[72:73], v[68:69], v[66:67] op_sel_hi:[0,1,1]
	ds_read_b128 v[66:69], v2
	v_mov_b32_e32 v62, v59
	s_waitcnt lgkmcnt(0)
	v_fmac_f32_e32 v0, v72, v66
	v_add_co_u32_e32 v72, vcc, s40, v80
	s_nop 1
	v_addc_co_u32_e32 v73, vcc, -1, v81, vcc
	s_waitcnt vmcnt(0)
	v_mov_b32_e32 v2, v115
	s_waitcnt vmcnt(0)
	v_pk_fma_f32 v[6:7], v[2:3], v[6:7], v[70:71] op_sel_hi:[0,1,1]
	v_pk_fma_f32 v[10:11], v[2:3], v[14:15], v[82:83] op_sel_hi:[0,1,1]
	v_pk_fma_f32 v[14:15], v[2:3], v[22:23], v[84:85] op_sel_hi:[0,1,1]
	v_pk_fma_f32 v[18:19], v[2:3], v[30:31], v[86:87] op_sel_hi:[0,1,1]
	v_pk_fma_f32 v[22:23], v[2:3], v[38:39], v[88:89] op_sel_hi:[0,1,1]
	v_pk_fma_f32 v[26:27], v[2:3], v[46:47], v[90:91] op_sel_hi:[0,1,1]
	v_pk_fma_f32 v[30:31], v[2:3], v[54:55], v[92:93] op_sel_hi:[0,1,1]
	v_pk_fma_f32 v[34:35], v[2:3], v[62:63], v[94:95] op_sel_hi:[0,1,1]
	v_fmac_f32_e32 v0, v2, v67
	v_add_co_u32_e32 v2, vcc, s57, v80
	v_mov_b32_e32 v38, v4
	s_nop 0
	v_addc_co_u32_e32 v3, vcc, -1, v81, vcc
	s_waitcnt vmcnt(0)
	v_mov_b32_e32 v2, v116
	v_mov_b32_e32 v39, v8
	v_mov_b32_e32 v8, v5
	s_waitcnt vmcnt(0)
	v_pk_fma_f32 v[6:7], v[2:3], v[38:39], v[6:7] op_sel_hi:[0,1,1]
	v_mov_b32_e32 v38, v12
	v_mov_b32_e32 v39, v16
	v_pk_fma_f32 v[10:11], v[2:3], v[38:39], v[10:11] op_sel_hi:[0,1,1]
	v_mov_b32_e32 v38, v20
	v_mov_b32_e32 v39, v24
	v_pk_fma_f32 v[38:39], v[2:3], v[38:39], v[14:15] op_sel_hi:[0,1,1]
	v_mov_b32_e32 v14, v28
	v_mov_b32_e32 v15, v32
	v_pk_fma_f32 v[18:19], v[2:3], v[14:15], v[18:19] op_sel_hi:[0,1,1]
	v_mov_b32_e32 v14, v36
	v_mov_b32_e32 v15, v40
	v_pk_fma_f32 v[42:43], v[2:3], v[14:15], v[22:23] op_sel_hi:[0,1,1]
	v_mov_b32_e32 v14, v44
	v_mov_b32_e32 v15, v48
	v_pk_fma_f32 v[26:27], v[2:3], v[14:15], v[26:27] op_sel_hi:[0,1,1]
	v_mov_b32_e32 v14, v52
	v_mov_b32_e32 v15, v56
	v_pk_fma_f32 v[50:51], v[2:3], v[14:15], v[30:31] op_sel_hi:[0,1,1]
	v_mov_b32_e32 v14, v60
	v_mov_b32_e32 v15, v64
	v_pk_fma_f32 v[34:35], v[2:3], v[14:15], v[34:35] op_sel_hi:[0,1,1]
	v_fmac_f32_e32 v0, v2, v68
	s_waitcnt vmcnt(0)
	v_mov_b32_e32 v2, v117
	v_mov_b32_e32 v16, v13
	v_mov_b32_e32 v24, v21
	v_mov_b32_e32 v32, v29
	v_mov_b32_e32 v40, v37
	v_mov_b32_e32 v48, v45
	v_mov_b32_e32 v56, v53
	v_mov_b32_e32 v64, v61
	v_lshl_add_u64 v[80:81], v[80:81], 0, s[28:29]
	s_waitcnt vmcnt(0)
	v_pk_fma_f32 v[14:15], v[2:3], v[8:9], v[6:7] op_sel_hi:[0,1,1]
	v_pk_fma_f32 v[22:23], v[2:3], v[16:17], v[10:11] op_sel_hi:[0,1,1]
	v_pk_fma_f32 v[30:31], v[2:3], v[24:25], v[38:39] op_sel_hi:[0,1,1]
	v_pk_fma_f32 v[38:39], v[2:3], v[32:33], v[18:19] op_sel_hi:[0,1,1]
	v_pk_fma_f32 v[46:47], v[2:3], v[40:41], v[42:43] op_sel_hi:[0,1,1]
	v_pk_fma_f32 v[54:55], v[2:3], v[48:49], v[26:27] op_sel_hi:[0,1,1]
	v_pk_fma_f32 v[62:63], v[2:3], v[56:57], v[50:51] op_sel_hi:[0,1,1]
	v_pk_fma_f32 v[70:71], v[2:3], v[64:65], v[34:35] op_sel_hi:[0,1,1]
	v_fmac_f32_e32 v0, v2, v69
	s_cbranch_scc0 .LBB0_1207
	ds_write2_b32 v103, v14, v15 offset1:16
	ds_write2_b32 v103, v22, v23 offset0:32 offset1:48
	ds_write2_b32 v103, v30, v31 offset0:64 offset1:80
	ds_write2_b32 v103, v38, v39 offset0:96 offset1:112
	ds_write2_b32 v103, v46, v47 offset0:128 offset1:144
	ds_write2_b32 v103, v54, v55 offset0:160 offset1:176
	ds_write2_b32 v103, v62, v63 offset0:192 offset1:208
	ds_write2_b32 v103, v70, v71 offset0:224 offset1:240
	ds_write_b32 v103, v0 offset:1024
	s_waitcnt lgkmcnt(0)
	s_barrier
	s_and_saveexec_b64 s[28:29], s[2:3]
	s_cbranch_execz .LBB0_1197
	s_lshl_b32 s30, s18, 4
	s_ashr_i32 s31, s30, 31
	v_lshl_add_u64 v[2:3], s[30:31], 2, v[76:77]
	s_mov_b64 s[34:35], -1
	v_mov_b32_e32 v0, v74
	s_and_saveexec_b64 s[30:31], s[8:9]
	s_cbranch_execz .LBB0_1213
	s_mov_b64 s[34:35], 0
	v_mov_b32_e32 v0, v99
	v_mov_b64_e32 v[4:5], v[74:75]
